# ff1, ff2, w_out GEMM loops now also use direct HBM->LDS loads (split-step, double-buffered B), no register staging
# speedup vs baseline: 1.0575x; 1.0047x over previous
.LBB0_11:
	s_mul_hi_i32 s24, s26, 0x2e8ba2e9
	s_lshr_b32 s25, s24, 31
	s_ashr_i32 s24, s24, 1
	s_add_i32 s34, s24, s25
	s_mul_i32 s24, s34, -11
	s_abs_i32 s25, s34
	v_writelane_b32 v236, s26, 36
	s_add_i32 s5, s24, s26
	s_mul_hi_u32 s26, s25, s46
	s_mul_i32 s28, s26, s15
	s_ashr_i32 s35, s34, 31
	s_sub_i32 s25, s25, s28
	s_xor_b32 s24, s35, s14
	s_add_i32 s28, s26, 1
	s_sub_i32 s29, s25, s15
	s_cmp_ge_u32 s25, s15
	s_cselect_b32 s26, s28, s26
	s_cselect_b32 s25, s29, s25
	s_add_i32 s28, s26, 1
	s_cmp_ge_u32 s25, s15
	s_cselect_b32 s25, s28, s26
	s_xor_b32 s25, s25, s24
	s_sub_i32 s4, s25, s24
	s_mov_b32 s0, s4
	v_writelane_b32 v236, s0, 37
	v_readlane_b32 s36, v240, 14
	v_readlane_b32 s37, v240, 15
	v_writelane_b32 v236, s1, 38
	v_writelane_b32 v236, s34, 39
	s_mul_i32 s0, s4, s37
	s_mov_b64 s[24:25], -1
	v_writelane_b32 v236, s35, 40
	v_writelane_b32 v236, s0, 41
	s_sub_i32 s0, s34, s0
	v_writelane_b32 v236, s0, 43
	s_ashr_i32 s0, s0, 31
	v_writelane_b32 v236, s0, 45
	s_cmp_lt_i32 s5, 5
	v_readlane_b32 s38, v240, 16
	v_readlane_b32 s39, v240, 17
	v_writelane_b32 v236, s5, 47
	s_cbranch_scc1 .LBB0_139
	v_readlane_b32 s0, v236, 45
	s_mul_i32 s24, s16, s0
	v_readlane_b32 s0, v236, 43
	s_mul_hi_u32 s25, s16, s0
	s_add_i32 s24, s25, s24
	s_mul_i32 s25, s17, s0
	s_add_i32 s41, s24, s25
	s_mul_i32 s40, s16, s0
	v_readlane_b32 s0, v236, 47
	s_cmp_lt_i32 s0, 8
	s_mov_b64 s[24:25], -1
	s_cbranch_scc1 .LBB0_56
	v_readlane_b32 s0, v236, 47
	s_cmp_lt_i32 s0, 9
	s_cbranch_scc1 .LBB0_51
	v_readlane_b32 s0, v236, 47
	s_cmp_lt_i32 s0, 10
	s_cbranch_scc1 .LBB0_33
	v_readlane_b32 s0, v236, 47
	s_cmp_eq_u32 s0, 10
	s_cbranch_scc0 .LBB0_32
	s_waitcnt lgkmcnt(2)
	v_mov_b32_e32 v48, v184
	s_mov_b32 s24, s87
	s_and_b32 s25, s24, 7
	v_readlane_b32 s0, v236, 16
	s_mul_i32 s25, s25, s0
	s_ashr_i32 s24, s24, 3
	s_add_i32 s28, s25, s24
	s_cmp_ge_i32 s28, s18
	s_cbranch_scc1 .LBB0_32
	v_readlane_b32 s0, v236, 37
	s_lshl_b32 s24, s0, 23
	v_readlane_b32 s44, v239, 34
	v_readlane_b32 s1, v236, 38
	s_and_b32 s24, s24, 0x800000
	v_readlane_b32 s54, v239, 44
	v_readlane_b32 s55, v239, 45
	s_add_u32 s26, s54, s24
	v_readlane_b32 s0, v239, 18
	s_addc_u32 s33, s55, 0
	s_lshl_b64 s[24:25], s[40:41], 2
	v_readlane_b32 s4, v239, 22
	v_readlane_b32 s5, v239, 23
	s_add_u32 s24, s4, s24
	s_addc_u32 s25, s5, s25
	s_ashr_i32 s29, s28, 31
	s_lshr_b32 s29, s29, 26
	s_add_i32 s29, s28, s29
	s_ashr_i32 s34, s29, 6
	s_andn2_b32 s29, s29, 63
	s_sub_i32 s29, s28, s29
	s_lshl_b32 s35, s34, 3
	s_ashr_i32 s34, s29, 3
	s_and_b32 s29, s28, 7
	v_readlane_b32 s1, v239, 19
	v_readlane_b32 s2, v239, 20
	v_readlane_b32 s3, v239, 21
	v_readlane_b32 s6, v239, 24
	v_readlane_b32 s7, v239, 25
	v_readlane_b32 s8, v239, 26
	v_readlane_b32 s9, v239, 27
	v_readlane_b32 s10, v239, 28
	v_readlane_b32 s11, v239, 29
	v_readlane_b32 s12, v239, 30
	v_readlane_b32 s13, v239, 31
	v_readlane_b32 s14, v239, 32
	v_readlane_b32 s15, v239, 33
	s_or_b32 s36, s35, s29
	s_ashr_i32 s37, s36, 31
	v_readlane_b32 s0, v237, 30
	s_waitcnt vmcnt(17)
	v_mov_b32_e32 v4, v184
	s_lshl_b64 s[36:37], s[36:37], 21
	v_readlane_b32 s12, v237, 42
	v_readlane_b32 s13, v237, 43
	v_ashrrev_i32_e32 v0, 3, v4
	s_add_u32 s36, s12, s36
	v_ashrrev_i32_e32 v1, 31, v0
	s_addc_u32 s37, s13, s37
	v_lshlrev_b64 v[0:1], 13, v[0:1]
	v_lshlrev_b32_e32 v4, 4, v4
	v_lshl_add_u64 v[2:3], s[36:37], 0, v[0:1]
	v_and_b32_e32 v176, 0x70, v4
	s_mov_b32 s38, 0x40000
	s_waitcnt vmcnt(16)
	v_lshl_add_u64 v[28:29], v[2:3], 0, v[176:177]
	v_add_co_u32_e32 v4, vcc, s38, v28
	s_mov_b32 s29, 0x80000
	s_nop 0
	v_addc_co_u32_e32 v5, vcc, 0, v29, vcc
	v_add_co_u32_e32 v8, vcc, s29, v28
	s_mov_b32 s29, 0xc0000
	s_nop 0
	v_addc_co_u32_e32 v9, vcc, 0, v29, vcc
	v_add_co_u32_e32 v12, vcc, s29, v28
	s_mov_b32 s29, 0x100000
	s_nop 0
	v_addc_co_u32_e32 v13, vcc, 0, v29, vcc
	s_waitcnt lgkmcnt(0)
	v_add_co_u32_e32 v16, vcc, s29, v28
	s_ashr_i32 s35, s34, 31
	s_nop 0
	v_addc_co_u32_e32 v17, vcc, 0, v29, vcc
	s_mov_b32 s29, 0x140000
	s_lshl_b64 s[34:35], s[34:35], 20
	v_add_co_u32_e32 v20, vcc, s29, v28
	s_add_u32 s34, s26, s34
	s_nop 0
	v_addc_co_u32_e32 v21, vcc, 0, v29, vcc
	s_addc_u32 s35, s33, s35
	v_add_co_u32_e32 v24, vcc, 0x180000, v28
	v_lshl_add_u64 v[0:1], s[34:35], 0, v[0:1]
	s_nop 0
	v_addc_co_u32_e32 v25, vcc, 0, v29, vcc
	v_lshl_add_u64 v[44:45], v[0:1], 0, v[176:177]
	s_mov_b32 m0, -1
	global_load_dwordx4 v[0:3], v[28:29], off
	v_add_co_u32_e32 v28, vcc, 0x1c0000, v28
	global_load_dwordx4 v[4:7], v[4:5], off
	s_nop 0
	global_load_dwordx4 v[8:11], v[8:9], off
	v_addc_co_u32_e32 v29, vcc, 0, v29, vcc
	v_add_co_u32_e32 v36, vcc, s38, v44
	global_load_dwordx4 v[12:15], v[12:13], off
	s_nop 0
	global_load_dwordx4 v[16:19], v[16:17], off
	v_addc_co_u32_e32 v37, vcc, 0, v45, vcc
	v_add_co_u32_e32 v40, vcc, 0x80000, v44
	global_load_dwordx4 v[20:23], v[20:21], off
	s_nop 0
	global_load_dwordx4 v[24:27], v[24:25], off
	v_addc_co_u32_e32 v41, vcc, 0, v45, vcc
	global_load_dwordx4 v[28:31], v[28:29], off
	s_nop 0
	global_load_dwordx4 v[32:35], v[44:45], off
	v_add_co_u32_e32 v44, vcc, 0xc0000, v44
	global_load_dwordx4 v[36:39], v[36:37], off
	s_nop 0
	global_load_dwordx4 v[40:43], v[40:41], off
	v_addc_co_u32_e32 v45, vcc, 0, v45, vcc
	global_load_dwordx4 v[44:47], v[44:45], off
	s_waitcnt vmcnt(27)
	v_lshrrev_b32_e32 v49, 2, v48
	v_and_b32_e32 v49, 12, v49
	v_and_b32_e32 v179, 0xffffff8f, v48
	v_and_or_b32 v213, v48, 64, v49
	v_readlane_b32 s45, v239, 35
	v_readlane_b32 s46, v239, 36
	v_readlane_b32 s47, v239, 37
	v_readlane_b32 s48, v239, 38
	v_readlane_b32 s49, v239, 39
	v_readlane_b32 s50, v239, 40
	v_readlane_b32 s51, v239, 41
	v_readlane_b32 s52, v239, 42
	v_readlane_b32 s53, v239, 43
	v_readlane_b32 s56, v239, 46
	v_readlane_b32 s57, v239, 47
	v_readlane_b32 s58, v239, 48
	v_readlane_b32 s59, v239, 49
	v_readlane_b32 s1, v237, 31
	v_readlane_b32 s2, v237, 32
	v_readlane_b32 s3, v237, 33
	v_readlane_b32 s4, v237, 34
	v_readlane_b32 s5, v237, 35
	v_readlane_b32 s6, v237, 36
	v_readlane_b32 s7, v237, 37
	v_readlane_b32 s8, v237, 38
	v_readlane_b32 s9, v237, 39
	v_readlane_b32 s10, v237, 40
	v_readlane_b32 s11, v237, 41
	v_readlane_b32 s14, v237, 44
	v_readlane_b32 s15, v237, 45
	s_branch .LBB0_19

.LBB0_23:
	s_cmpk_gt_u32 s45, 0xfbf
	s_cselect_b64 s[28:29], -1, 0
	s_cmp_lg_u32 s45, 0
	s_cbranch_scc1 .Ls_nosetup_ff2
	v_add_u32_e32 v176, v182, v180
	v_add_u32_e32 v243, v182, v183
	v_add_u32_e32 v241, v181, v180
	v_add_u32_e32 v242, v181, v183
	v_lshrrev_b32_e32 v180, 3, v184
	v_and_b32_e32 v181, 7, v184
	v_bfe_u32 v183, v184, 4, 3
	v_xor_b32_e32 v181, v181, v183
	v_lshlrev_b32_e32 v180, 13, v180
	v_lshl_add_u32 v180, v181, 4, v180
	v_readfirstlane_b32 s100, v184
	s_lshl_b32 s100, s100, 4
	s_cmp_lg_u32 m0, -1
	s_cbranch_scc1 .Ls_nosetup_ff2
	s_mov_b32 m0, 0
	s_waitcnt vmcnt(0)
	ds_write_b128 v214, v[0:3]
	ds_write_b128 v214, v[4:7] offset:4096
	ds_write_b128 v214, v[8:11] offset:8192
	ds_write_b128 v214, v[12:15] offset:12288
	ds_write_b128 v214, v[16:19] offset:16384
	ds_write_b128 v214, v[20:23] offset:20480
	ds_write_b128 v214, v[24:27] offset:24576
	ds_write_b128 v214, v[28:31] offset:28672
	ds_write_b128 v214, v[32:35] offset:32768
	ds_write_b128 v214, v[36:39] offset:36864
	ds_write_b128 v214, v[40:43] offset:40960
	ds_write_b128 v214, v[44:47] offset:45056
	s_waitcnt lgkmcnt(0)
	s_barrier
.Ls_nosetup_ff2:
	s_lshl_b32 s101, s45, 1
	s_add_u32 s84, s50, s101
	s_addc_u32 s85, s51, 0
	s_add_i32 s101, s45, 64
	s_cmpk_ge_u32 s101, 0x1000
	s_cselect_b32 s98, 0x1000, 0
	s_cselect_b32 s99, s94, 0
	s_sub_u32 s101, s101, s98
	s_lshl_b32 s101, s101, 1
	s_cmp_lg_u32 s99, 0
	s_cselect_b64 s[86:87], s[38:39], s[50:51]
	s_cselect_b64 s[34:35], s[42:43], s[92:93]
	s_add_u32 s86, s86, s101
	s_addc_u32 s87, s87, 0
	s_add_u32 s34, s34, s101
	s_addc_u32 s35, s35, 0
	s_lshr_b32 s101, s45, 6
	s_add_i32 s101, s101, 1
	s_and_b32 s101, s101, 1
	s_lshl_b32 s101, s101, 14
	s_add_u32 s101, s101, s100
	s_add_u32 s101, s101, 0x8000
	s_add_u32 s98, s84, 0x80000
	s_addc_u32 s99, s85, 0
	s_add_u32 m0, s100, 0x2000
	s_nop 0
	global_load_lds_dwordx4 v180, s[98:99]
	s_add_u32 s98, s84, 0xc0000
	s_addc_u32 s99, s85, 0
	s_add_u32 m0, s100, 0x3000
	s_nop 0
	global_load_lds_dwordx4 v180, s[98:99]
	s_add_u32 s98, s84, 0x180000
	s_addc_u32 s99, s85, 0
	s_add_u32 m0, s100, 0x6000
	s_nop 0
	global_load_lds_dwordx4 v180, s[98:99]
	s_add_u32 s98, s84, 0x1c0000
	s_addc_u32 s99, s85, 0
	s_add_u32 m0, s100, 0x7000
	s_nop 0
	global_load_lds_dwordx4 v180, s[98:99]
	s_add_u32 s98, s34, 0x0
	s_addc_u32 s99, s35, 0
	s_add_u32 m0, s101, 0x0
	s_nop 0
	global_load_lds_dwordx4 v180, s[98:99]
	s_add_u32 s98, s34, 0x40000
	s_addc_u32 s99, s35, 0
	s_add_u32 m0, s101, 0x1000
	s_nop 0
	global_load_lds_dwordx4 v180, s[98:99]
	ds_read_b128 v[216:219], v176 offset:32768
	ds_read_b128 v[232:235], v241
	ds_read_b128 v[220:223], v176 offset:34816
	ds_read_b128 v[224:227], v176 offset:36864
	ds_read_b128 v[228:231], v176 offset:38912
	ds_read_b128 v[244:247], v241 offset:2048
	ds_read_b128 v[248:251], v241 offset:4096
	ds_read_b128 v[252:255], v241 offset:6144
	s_waitcnt lgkmcnt(6)
	v_mfma_f32_16x16x32_bf16 v[172:175], v[216:219], v[232:235], v[172:175]
	s_waitcnt lgkmcnt(5)
	v_mfma_f32_16x16x32_bf16 v[168:171], v[220:223], v[232:235], v[168:171]
	s_waitcnt lgkmcnt(4)
	v_mfma_f32_16x16x32_bf16 v[164:167], v[224:227], v[232:235], v[164:167]
	s_waitcnt lgkmcnt(3)
	v_mfma_f32_16x16x32_bf16 v[160:163], v[228:231], v[232:235], v[160:163]
	ds_read_b128 v[232:235], v242
	s_waitcnt lgkmcnt(3)
	v_mfma_f32_16x16x32_bf16 v[156:159], v[216:219], v[244:247], v[156:159]
	v_mfma_f32_16x16x32_bf16 v[152:155], v[220:223], v[244:247], v[152:155]
	v_mfma_f32_16x16x32_bf16 v[148:151], v[224:227], v[244:247], v[148:151]
	v_mfma_f32_16x16x32_bf16 v[144:147], v[228:231], v[244:247], v[144:147]
	ds_read_b128 v[244:247], v242 offset:2048
	s_waitcnt lgkmcnt(3)
	v_mfma_f32_16x16x32_bf16 v[140:143], v[216:219], v[248:251], v[140:143]
	s_waitcnt lgkmcnt(2)
	v_mfma_f32_16x16x32_bf16 v[124:127], v[216:219], v[252:255], v[124:127]
	ds_read_b128 v[216:219], v243 offset:32768
	v_mfma_f32_16x16x32_bf16 v[136:139], v[220:223], v[248:251], v[136:139]
	v_mfma_f32_16x16x32_bf16 v[120:123], v[220:223], v[252:255], v[120:123]
	ds_read_b128 v[220:223], v243 offset:34816
	v_mfma_f32_16x16x32_bf16 v[132:135], v[224:227], v[248:251], v[132:135]
	v_mfma_f32_16x16x32_bf16 v[116:119], v[224:227], v[252:255], v[116:119]
	ds_read_b128 v[224:227], v243 offset:36864
	v_mfma_f32_16x16x32_bf16 v[128:131], v[228:231], v[248:251], v[128:131]
	v_mfma_f32_16x16x32_bf16 v[112:115], v[228:231], v[252:255], v[112:115]
	ds_read_b128 v[228:231], v243 offset:38912
	ds_read_b128 v[248:251], v242 offset:4096
	ds_read_b128 v[252:255], v242 offset:6144
	s_waitcnt lgkmcnt(5)
	v_mfma_f32_16x16x32_bf16 v[172:175], v[216:219], v[232:235], v[172:175]
	v_mfma_f32_16x16x32_bf16 v[156:159], v[216:219], v[244:247], v[156:159]
	s_waitcnt lgkmcnt(4)
	v_mfma_f32_16x16x32_bf16 v[168:171], v[220:223], v[232:235], v[168:171]
	v_mfma_f32_16x16x32_bf16 v[152:155], v[220:223], v[244:247], v[152:155]
	s_waitcnt lgkmcnt(3)
	v_mfma_f32_16x16x32_bf16 v[164:167], v[224:227], v[232:235], v[164:167]
	v_mfma_f32_16x16x32_bf16 v[148:151], v[224:227], v[244:247], v[148:151]
	s_waitcnt lgkmcnt(2)
	v_mfma_f32_16x16x32_bf16 v[160:163], v[228:231], v[232:235], v[160:163]
	v_mfma_f32_16x16x32_bf16 v[144:147], v[228:231], v[244:247], v[144:147]
	s_waitcnt lgkmcnt(1)
	v_mfma_f32_16x16x32_bf16 v[140:143], v[216:219], v[248:251], v[140:143]
	v_mfma_f32_16x16x32_bf16 v[136:139], v[220:223], v[248:251], v[136:139]
	v_mfma_f32_16x16x32_bf16 v[132:135], v[224:227], v[248:251], v[132:135]
	v_mfma_f32_16x16x32_bf16 v[128:131], v[228:231], v[248:251], v[128:131]
	s_waitcnt vmcnt(0)
	s_waitcnt lgkmcnt(0)
	s_barrier
	v_mfma_f32_16x16x32_bf16 v[124:127], v[216:219], v[252:255], v[124:127]
	v_mfma_f32_16x16x32_bf16 v[120:123], v[220:223], v[252:255], v[120:123]
	v_mfma_f32_16x16x32_bf16 v[116:119], v[224:227], v[252:255], v[116:119]
	v_mfma_f32_16x16x32_bf16 v[112:115], v[228:231], v[252:255], v[112:115]
	s_add_u32 s98, s86, 0x0
	s_addc_u32 s99, s87, 0
	s_add_u32 m0, s100, 0x0
	s_nop 0
	global_load_lds_dwordx4 v180, s[98:99]
	s_add_u32 s98, s86, 0x40000
	s_addc_u32 s99, s87, 0
	s_add_u32 m0, s100, 0x1000
	s_nop 0
	global_load_lds_dwordx4 v180, s[98:99]
	s_add_u32 s98, s86, 0x100000
	s_addc_u32 s99, s87, 0
	s_add_u32 m0, s100, 0x4000
	s_nop 0
	global_load_lds_dwordx4 v180, s[98:99]
	s_add_u32 s98, s86, 0x140000
	s_addc_u32 s99, s87, 0
	s_add_u32 m0, s100, 0x5000
	s_nop 0
	global_load_lds_dwordx4 v180, s[98:99]
	s_add_u32 s98, s34, 0x80000
	s_addc_u32 s99, s35, 0
	s_add_u32 m0, s101, 0x2000
	s_nop 0
	global_load_lds_dwordx4 v180, s[98:99]
	s_add_u32 s98, s34, 0xc0000
	s_addc_u32 s99, s35, 0
	s_add_u32 m0, s101, 0x3000
	s_nop 0
	global_load_lds_dwordx4 v180, s[98:99]
	ds_read_b128 v[216:219], v176 offset:32768
	ds_read_b128 v[232:235], v241 offset:8192
	ds_read_b128 v[220:223], v176 offset:34816
	ds_read_b128 v[224:227], v176 offset:36864
	ds_read_b128 v[228:231], v176 offset:38912
	ds_read_b128 v[244:247], v241 offset:10240
	ds_read_b128 v[248:251], v241 offset:12288
	ds_read_b128 v[252:255], v241 offset:14336
	s_waitcnt lgkmcnt(6)
	v_mfma_f32_16x16x32_bf16 v[108:111], v[216:219], v[232:235], v[108:111]
	s_waitcnt lgkmcnt(5)
	v_mfma_f32_16x16x32_bf16 v[104:107], v[220:223], v[232:235], v[104:107]
	s_waitcnt lgkmcnt(4)
	v_mfma_f32_16x16x32_bf16 v[100:103], v[224:227], v[232:235], v[100:103]
	s_waitcnt lgkmcnt(3)
	v_mfma_f32_16x16x32_bf16 v[96:99], v[228:231], v[232:235], v[96:99]
	ds_read_b128 v[232:235], v242 offset:8192
	s_waitcnt lgkmcnt(3)
	v_mfma_f32_16x16x32_bf16 v[92:95], v[216:219], v[244:247], v[92:95]
	v_mfma_f32_16x16x32_bf16 v[88:91], v[220:223], v[244:247], v[88:91]
	v_mfma_f32_16x16x32_bf16 v[84:87], v[224:227], v[244:247], v[84:87]
	v_mfma_f32_16x16x32_bf16 v[80:83], v[228:231], v[244:247], v[80:83]
	ds_read_b128 v[244:247], v242 offset:10240
	s_waitcnt lgkmcnt(3)
	v_mfma_f32_16x16x32_bf16 v[76:79], v[216:219], v[248:251], v[76:79]
	s_waitcnt lgkmcnt(2)
	v_mfma_f32_16x16x32_bf16 v[60:63], v[216:219], v[252:255], v[60:63]
	ds_read_b128 v[216:219], v243 offset:32768
	v_mfma_f32_16x16x32_bf16 v[72:75], v[220:223], v[248:251], v[72:75]
	v_mfma_f32_16x16x32_bf16 v[56:59], v[220:223], v[252:255], v[56:59]
	ds_read_b128 v[220:223], v243 offset:34816
	v_mfma_f32_16x16x32_bf16 v[68:71], v[224:227], v[248:251], v[68:71]
	v_mfma_f32_16x16x32_bf16 v[52:55], v[224:227], v[252:255], v[52:55]
	ds_read_b128 v[224:227], v243 offset:36864
	v_mfma_f32_16x16x32_bf16 v[64:67], v[228:231], v[248:251], v[64:67]
	v_mfma_f32_16x16x32_bf16 v[48:51], v[228:231], v[252:255], v[48:51]
	ds_read_b128 v[228:231], v243 offset:38912
	ds_read_b128 v[248:251], v242 offset:12288
	ds_read_b128 v[252:255], v242 offset:14336
	s_waitcnt lgkmcnt(5)
	v_mfma_f32_16x16x32_bf16 v[108:111], v[216:219], v[232:235], v[108:111]
	v_mfma_f32_16x16x32_bf16 v[92:95], v[216:219], v[244:247], v[92:95]
	s_waitcnt lgkmcnt(4)
	v_mfma_f32_16x16x32_bf16 v[104:107], v[220:223], v[232:235], v[104:107]
	v_mfma_f32_16x16x32_bf16 v[88:91], v[220:223], v[244:247], v[88:91]
	s_waitcnt lgkmcnt(3)
	v_mfma_f32_16x16x32_bf16 v[100:103], v[224:227], v[232:235], v[100:103]
	v_mfma_f32_16x16x32_bf16 v[84:87], v[224:227], v[244:247], v[84:87]
	s_waitcnt lgkmcnt(2)
	v_mfma_f32_16x16x32_bf16 v[96:99], v[228:231], v[232:235], v[96:99]
	v_mfma_f32_16x16x32_bf16 v[80:83], v[228:231], v[244:247], v[80:83]
	s_waitcnt lgkmcnt(1)
	v_mfma_f32_16x16x32_bf16 v[76:79], v[216:219], v[248:251], v[76:79]
	v_mfma_f32_16x16x32_bf16 v[72:75], v[220:223], v[248:251], v[72:75]
	v_mfma_f32_16x16x32_bf16 v[68:71], v[224:227], v[248:251], v[68:71]
	v_mfma_f32_16x16x32_bf16 v[64:67], v[228:231], v[248:251], v[64:67]
	s_waitcnt vmcnt(0)
	s_waitcnt lgkmcnt(0)
	s_barrier
	v_mfma_f32_16x16x32_bf16 v[60:63], v[216:219], v[252:255], v[60:63]
	v_mfma_f32_16x16x32_bf16 v[56:59], v[220:223], v[252:255], v[56:59]
	v_mfma_f32_16x16x32_bf16 v[52:55], v[224:227], v[252:255], v[52:55]
	v_mfma_f32_16x16x32_bf16 v[48:51], v[228:231], v[252:255], v[48:51]
	v_xor_b32_e32 v176, 0x4000, v176
	v_xor_b32_e32 v243, 0x4000, v243
	s_add_i32 s45, s45, 64
	s_andn2_b64 vcc, exec, s[28:29]
	s_mov_b32 s85, 0x800000
	s_cbranch_vccz .LBB0_18
	s_branch .LBB0_23

.LBB0_33:
	s_andn2_b64 vcc, exec, s[24:25]
	s_cbranch_vccnz .LBB0_50
	s_waitcnt lgkmcnt(2)
	v_mov_b32_e32 v48, v184
	s_mov_b32 s24, s87
	s_and_b32 s25, s24, 7
	v_readlane_b32 s0, v236, 16
	s_mul_i32 s25, s25, s0
	s_ashr_i32 s24, s24, 3
	s_add_i32 s28, s25, s24
	v_readlane_b32 s0, v239, 50
	s_cmp_ge_i32 s28, s0
	s_cbranch_scc1 .LBB0_50
	s_ashr_i32 s24, s28, 31
	s_lshr_b32 s24, s24, 24
	s_add_i32 s24, s28, s24
	s_ashr_i32 s25, s24, 8
	s_lshl_b32 s25, s25, 3
	s_and_b32 s26, s28, 7
	s_and_b32 s24, s24, 0xffffff00
	s_or_b32 s34, s25, s26
	s_sub_i32 s24, s28, s24
	s_ashr_i32 s35, s34, 31
	s_waitcnt vmcnt(17)
	v_mov_b32_e32 v4, v184
	s_ashr_i32 s24, s24, 3
	s_lshl_b64 s[34:35], s[34:35], 19
	s_add_u32 s34, s76, s34
	v_ashrrev_i32_e32 v0, 3, v4
	v_ashrrev_i32_e32 v1, 31, v0
	s_addc_u32 s35, s77, s35
	v_lshlrev_b64 v[0:1], 11, v[0:1]
	v_lshlrev_b32_e32 v4, 4, v4
	v_lshl_add_u64 v[2:3], s[34:35], 0, v[0:1]
	v_and_b32_e32 v176, 0x70, v4
	s_mov_b32 s1, 0x10000
	s_waitcnt vmcnt(16)
	v_lshl_add_u64 v[28:29], v[2:3], 0, v[176:177]
	v_add_co_u32_e32 v4, vcc, s1, v28
	s_mov_b32 s2, 0x20000
	s_nop 0
	v_addc_co_u32_e32 v5, vcc, 0, v29, vcc
	v_add_co_u32_e32 v8, vcc, s2, v28
	s_mov_b32 s3, 0x30000
	s_nop 0
	v_addc_co_u32_e32 v9, vcc, 0, v29, vcc
	v_add_co_u32_e32 v12, vcc, s3, v28
	s_mov_b32 s0, 0x40000
	s_nop 0
	v_addc_co_u32_e32 v13, vcc, 0, v29, vcc
	s_waitcnt lgkmcnt(0)
	v_add_co_u32_e32 v16, vcc, s0, v28
	s_ashr_i32 s25, s24, 31
	v_readlane_b32 s44, v239, 34
	v_addc_co_u32_e32 v17, vcc, 0, v29, vcc
	s_mov_b32 s0, 0x50000
	s_lshl_b64 s[24:25], s[24:25], 18
	v_readlane_b32 s52, v239, 42
	v_add_co_u32_e32 v20, vcc, s0, v28
	v_readlane_b32 s53, v239, 43
	s_add_u32 s24, s52, s24
	v_addc_co_u32_e32 v21, vcc, 0, v29, vcc
	s_addc_u32 s25, s53, s25
	v_add_co_u32_e32 v24, vcc, 0x60000, v28
	v_lshl_add_u64 v[0:1], s[24:25], 0, v[0:1]
	s_nop 0
	v_addc_co_u32_e32 v25, vcc, 0, v29, vcc
	v_lshl_add_u64 v[44:45], v[0:1], 0, v[176:177]
	s_mov_b32 m0, -1
	global_load_dwordx4 v[0:3], v[28:29], off
	v_add_co_u32_e32 v28, vcc, 0x70000, v28
	global_load_dwordx4 v[4:7], v[4:5], off
	s_nop 0
	global_load_dwordx4 v[8:11], v[8:9], off
	v_addc_co_u32_e32 v29, vcc, 0, v29, vcc
	v_add_co_u32_e32 v36, vcc, s1, v44
	global_load_dwordx4 v[12:15], v[12:13], off
	s_nop 0
	global_load_dwordx4 v[16:19], v[16:17], off
	v_addc_co_u32_e32 v37, vcc, 0, v45, vcc
	v_add_co_u32_e32 v40, vcc, 0x20000, v44
	global_load_dwordx4 v[20:23], v[20:21], off
	s_nop 0
	global_load_dwordx4 v[24:27], v[24:25], off
	v_addc_co_u32_e32 v41, vcc, 0, v45, vcc
	global_load_dwordx4 v[28:31], v[28:29], off
	s_nop 0
	global_load_dwordx4 v[32:35], v[44:45], off
	v_add_co_u32_e32 v44, vcc, 0x30000, v44
	global_load_dwordx4 v[36:39], v[36:37], off
	s_nop 0
	global_load_dwordx4 v[40:43], v[40:41], off
	v_addc_co_u32_e32 v45, vcc, 0, v45, vcc
	global_load_dwordx4 v[44:47], v[44:45], off
	s_waitcnt vmcnt(27)
	v_lshrrev_b32_e32 v49, 2, v48
	v_and_b32_e32 v49, 12, v49
	v_and_b32_e32 v179, 0xffffff8f, v48
	v_and_or_b32 v182, v48, 64, v49
	v_readlane_b32 s45, v239, 35
	v_readlane_b32 s46, v239, 36
	v_readlane_b32 s47, v239, 37
	v_readlane_b32 s48, v239, 38
	v_readlane_b32 s49, v239, 39
	v_readlane_b32 s50, v239, 40
	v_readlane_b32 s51, v239, 41
	v_readlane_b32 s54, v239, 44
	v_readlane_b32 s55, v239, 45
	v_readlane_b32 s56, v239, 46
	v_readlane_b32 s57, v239, 47
	v_readlane_b32 s58, v239, 48
	v_readlane_b32 s59, v239, 49
	s_branch .LBB0_37

.LBB0_41:
	s_cmpk_gt_u32 s33, 0x3bf
	s_cselect_b64 s[28:29], -1, 0
	s_cmp_lg_u32 s33, 0
	s_cbranch_scc1 .Ls_nosetup_ff1
	v_add_u32_e32 v176, v183, v180
	v_add_u32_e32 v243, v183, v213
	v_add_u32_e32 v241, v181, v180
	v_add_u32_e32 v242, v181, v213
	v_lshrrev_b32_e32 v180, 3, v184
	v_and_b32_e32 v181, 7, v184
	v_bfe_u32 v213, v184, 4, 3
	v_xor_b32_e32 v181, v181, v213
	v_lshlrev_b32_e32 v180, 11, v180
	v_lshl_add_u32 v180, v181, 4, v180
	v_readfirstlane_b32 s100, v184
	s_lshl_b32 s100, s100, 4
	s_cmp_lg_u32 m0, -1
	s_cbranch_scc1 .Ls_nosetup_ff1
	s_mov_b32 m0, 0
	s_waitcnt vmcnt(0)
	ds_write_b128 v214, v[0:3]
	ds_write_b128 v214, v[4:7] offset:4096
	ds_write_b128 v214, v[8:11] offset:8192
	ds_write_b128 v214, v[12:15] offset:12288
	ds_write_b128 v214, v[16:19] offset:16384
	ds_write_b128 v214, v[20:23] offset:20480
	ds_write_b128 v214, v[24:27] offset:24576
	ds_write_b128 v214, v[28:31] offset:28672
	ds_write_b128 v214, v[32:35] offset:32768
	ds_write_b128 v214, v[36:39] offset:36864
	ds_write_b128 v214, v[40:43] offset:40960
	ds_write_b128 v214, v[44:47] offset:45056
	s_waitcnt lgkmcnt(0)
	s_barrier
.Ls_nosetup_ff1:
	s_lshl_b32 s101, s33, 1
	s_add_u32 s84, s46, s101
	s_addc_u32 s85, s47, 0
	s_add_i32 s101, s33, 64
	s_cmpk_ge_u32 s101, 0x400
	s_cselect_b32 s98, 0x400, 0
	s_cselect_b32 s99, s92, 0
	s_sub_u32 s101, s101, s98
	s_lshl_b32 s101, s101, 1
	s_cmp_lg_u32 s99, 0
	s_cselect_b64 s[86:87], s[36:37], s[46:47]
	s_cselect_b64 s[34:35], s[38:39], s[50:51]
	s_add_u32 s86, s86, s101
	s_addc_u32 s87, s87, 0
	s_add_u32 s34, s34, s101
	s_addc_u32 s35, s35, 0
	s_lshr_b32 s101, s33, 6
	s_add_i32 s101, s101, 1
	s_and_b32 s101, s101, 1
	s_lshl_b32 s101, s101, 14
	s_add_u32 s101, s101, s100
	s_add_u32 s101, s101, 0x8000
	s_add_u32 s98, s84, 0x20000
	s_addc_u32 s99, s85, 0
	s_add_u32 m0, s100, 0x2000
	s_nop 0
	global_load_lds_dwordx4 v180, s[98:99]
	s_add_u32 s98, s84, 0x30000
	s_addc_u32 s99, s85, 0
	s_add_u32 m0, s100, 0x3000
	s_nop 0
	global_load_lds_dwordx4 v180, s[98:99]
	s_add_u32 s98, s84, 0x60000
	s_addc_u32 s99, s85, 0
	s_add_u32 m0, s100, 0x6000
	s_nop 0
	global_load_lds_dwordx4 v180, s[98:99]
	s_add_u32 s98, s84, 0x70000
	s_addc_u32 s99, s85, 0
	s_add_u32 m0, s100, 0x7000
	s_nop 0
	global_load_lds_dwordx4 v180, s[98:99]
	s_add_u32 s98, s34, 0x0
	s_addc_u32 s99, s35, 0
	s_add_u32 m0, s101, 0x0
	s_nop 0
	global_load_lds_dwordx4 v180, s[98:99]
	s_add_u32 s98, s34, 0x10000
	s_addc_u32 s99, s35, 0
	s_add_u32 m0, s101, 0x1000
	s_nop 0
	global_load_lds_dwordx4 v180, s[98:99]
	ds_read_b128 v[216:219], v176 offset:32768
	ds_read_b128 v[232:235], v241
	ds_read_b128 v[220:223], v176 offset:34816
	ds_read_b128 v[224:227], v176 offset:36864
	ds_read_b128 v[228:231], v176 offset:38912
	ds_read_b128 v[244:247], v241 offset:2048
	ds_read_b128 v[248:251], v241 offset:4096
	ds_read_b128 v[252:255], v241 offset:6144
	s_waitcnt lgkmcnt(6)
	v_mfma_f32_16x16x32_bf16 v[172:175], v[216:219], v[232:235], v[172:175]
	s_waitcnt lgkmcnt(5)
	v_mfma_f32_16x16x32_bf16 v[168:171], v[220:223], v[232:235], v[168:171]
	s_waitcnt lgkmcnt(4)
	v_mfma_f32_16x16x32_bf16 v[164:167], v[224:227], v[232:235], v[164:167]
	s_waitcnt lgkmcnt(3)
	v_mfma_f32_16x16x32_bf16 v[160:163], v[228:231], v[232:235], v[160:163]
	ds_read_b128 v[232:235], v242
	s_waitcnt lgkmcnt(3)
	v_mfma_f32_16x16x32_bf16 v[156:159], v[216:219], v[244:247], v[156:159]
	v_mfma_f32_16x16x32_bf16 v[152:155], v[220:223], v[244:247], v[152:155]
	v_mfma_f32_16x16x32_bf16 v[148:151], v[224:227], v[244:247], v[148:151]
	v_mfma_f32_16x16x32_bf16 v[144:147], v[228:231], v[244:247], v[144:147]
	ds_read_b128 v[244:247], v242 offset:2048
	s_waitcnt lgkmcnt(3)
	v_mfma_f32_16x16x32_bf16 v[140:143], v[216:219], v[248:251], v[140:143]
	s_waitcnt lgkmcnt(2)
	v_mfma_f32_16x16x32_bf16 v[124:127], v[216:219], v[252:255], v[124:127]
	ds_read_b128 v[216:219], v243 offset:32768
	v_mfma_f32_16x16x32_bf16 v[136:139], v[220:223], v[248:251], v[136:139]
	v_mfma_f32_16x16x32_bf16 v[120:123], v[220:223], v[252:255], v[120:123]
	ds_read_b128 v[220:223], v243 offset:34816
	v_mfma_f32_16x16x32_bf16 v[132:135], v[224:227], v[248:251], v[132:135]
	v_mfma_f32_16x16x32_bf16 v[116:119], v[224:227], v[252:255], v[116:119]
	ds_read_b128 v[224:227], v243 offset:36864
	v_mfma_f32_16x16x32_bf16 v[128:131], v[228:231], v[248:251], v[128:131]
	v_mfma_f32_16x16x32_bf16 v[112:115], v[228:231], v[252:255], v[112:115]
	ds_read_b128 v[228:231], v243 offset:38912
	ds_read_b128 v[248:251], v242 offset:4096
	ds_read_b128 v[252:255], v242 offset:6144
	s_waitcnt lgkmcnt(5)
	v_mfma_f32_16x16x32_bf16 v[172:175], v[216:219], v[232:235], v[172:175]
	v_mfma_f32_16x16x32_bf16 v[156:159], v[216:219], v[244:247], v[156:159]
	s_waitcnt lgkmcnt(4)
	v_mfma_f32_16x16x32_bf16 v[168:171], v[220:223], v[232:235], v[168:171]
	v_mfma_f32_16x16x32_bf16 v[152:155], v[220:223], v[244:247], v[152:155]
	s_waitcnt lgkmcnt(3)
	v_mfma_f32_16x16x32_bf16 v[164:167], v[224:227], v[232:235], v[164:167]
	v_mfma_f32_16x16x32_bf16 v[148:151], v[224:227], v[244:247], v[148:151]
	s_waitcnt lgkmcnt(2)
	v_mfma_f32_16x16x32_bf16 v[160:163], v[228:231], v[232:235], v[160:163]
	v_mfma_f32_16x16x32_bf16 v[144:147], v[228:231], v[244:247], v[144:147]
	s_waitcnt lgkmcnt(1)
	v_mfma_f32_16x16x32_bf16 v[140:143], v[216:219], v[248:251], v[140:143]
	v_mfma_f32_16x16x32_bf16 v[136:139], v[220:223], v[248:251], v[136:139]
	v_mfma_f32_16x16x32_bf16 v[132:135], v[224:227], v[248:251], v[132:135]
	v_mfma_f32_16x16x32_bf16 v[128:131], v[228:231], v[248:251], v[128:131]
	s_waitcnt vmcnt(0)
	s_waitcnt lgkmcnt(0)
	s_barrier
	v_mfma_f32_16x16x32_bf16 v[124:127], v[216:219], v[252:255], v[124:127]
	v_mfma_f32_16x16x32_bf16 v[120:123], v[220:223], v[252:255], v[120:123]
	v_mfma_f32_16x16x32_bf16 v[116:119], v[224:227], v[252:255], v[116:119]
	v_mfma_f32_16x16x32_bf16 v[112:115], v[228:231], v[252:255], v[112:115]
	s_add_u32 s98, s86, 0x0
	s_addc_u32 s99, s87, 0
	s_add_u32 m0, s100, 0x0
	s_nop 0
	global_load_lds_dwordx4 v180, s[98:99]
	s_add_u32 s98, s86, 0x10000
	s_addc_u32 s99, s87, 0
	s_add_u32 m0, s100, 0x1000
	s_nop 0
	global_load_lds_dwordx4 v180, s[98:99]
	s_add_u32 s98, s86, 0x40000
	s_addc_u32 s99, s87, 0
	s_add_u32 m0, s100, 0x4000
	s_nop 0
	global_load_lds_dwordx4 v180, s[98:99]
	s_add_u32 s98, s86, 0x50000
	s_addc_u32 s99, s87, 0
	s_add_u32 m0, s100, 0x5000
	s_nop 0
	global_load_lds_dwordx4 v180, s[98:99]
	s_add_u32 s98, s34, 0x20000
	s_addc_u32 s99, s35, 0
	s_add_u32 m0, s101, 0x2000
	s_nop 0
	global_load_lds_dwordx4 v180, s[98:99]
	s_add_u32 s98, s34, 0x30000
	s_addc_u32 s99, s35, 0
	s_add_u32 m0, s101, 0x3000
	s_nop 0
	global_load_lds_dwordx4 v180, s[98:99]
	ds_read_b128 v[216:219], v176 offset:32768
	ds_read_b128 v[232:235], v241 offset:8192
	ds_read_b128 v[220:223], v176 offset:34816
	ds_read_b128 v[224:227], v176 offset:36864
	ds_read_b128 v[228:231], v176 offset:38912
	ds_read_b128 v[244:247], v241 offset:10240
	ds_read_b128 v[248:251], v241 offset:12288
	ds_read_b128 v[252:255], v241 offset:14336
	s_waitcnt lgkmcnt(6)
	v_mfma_f32_16x16x32_bf16 v[108:111], v[216:219], v[232:235], v[108:111]
	s_waitcnt lgkmcnt(5)
	v_mfma_f32_16x16x32_bf16 v[104:107], v[220:223], v[232:235], v[104:107]
	s_waitcnt lgkmcnt(4)
	v_mfma_f32_16x16x32_bf16 v[100:103], v[224:227], v[232:235], v[100:103]
	s_waitcnt lgkmcnt(3)
	v_mfma_f32_16x16x32_bf16 v[96:99], v[228:231], v[232:235], v[96:99]
	ds_read_b128 v[232:235], v242 offset:8192
	s_waitcnt lgkmcnt(3)
	v_mfma_f32_16x16x32_bf16 v[92:95], v[216:219], v[244:247], v[92:95]
	v_mfma_f32_16x16x32_bf16 v[88:91], v[220:223], v[244:247], v[88:91]
	v_mfma_f32_16x16x32_bf16 v[84:87], v[224:227], v[244:247], v[84:87]
	v_mfma_f32_16x16x32_bf16 v[80:83], v[228:231], v[244:247], v[80:83]
	ds_read_b128 v[244:247], v242 offset:10240
	s_waitcnt lgkmcnt(3)
	v_mfma_f32_16x16x32_bf16 v[76:79], v[216:219], v[248:251], v[76:79]
	s_waitcnt lgkmcnt(2)
	v_mfma_f32_16x16x32_bf16 v[60:63], v[216:219], v[252:255], v[60:63]
	ds_read_b128 v[216:219], v243 offset:32768
	v_mfma_f32_16x16x32_bf16 v[72:75], v[220:223], v[248:251], v[72:75]
	v_mfma_f32_16x16x32_bf16 v[56:59], v[220:223], v[252:255], v[56:59]
	ds_read_b128 v[220:223], v243 offset:34816
	v_mfma_f32_16x16x32_bf16 v[68:71], v[224:227], v[248:251], v[68:71]
	v_mfma_f32_16x16x32_bf16 v[52:55], v[224:227], v[252:255], v[52:55]
	ds_read_b128 v[224:227], v243 offset:36864
	v_mfma_f32_16x16x32_bf16 v[64:67], v[228:231], v[248:251], v[64:67]
	v_mfma_f32_16x16x32_bf16 v[48:51], v[228:231], v[252:255], v[48:51]
	ds_read_b128 v[228:231], v243 offset:38912
	ds_read_b128 v[248:251], v242 offset:12288
	ds_read_b128 v[252:255], v242 offset:14336
	s_waitcnt lgkmcnt(5)
	v_mfma_f32_16x16x32_bf16 v[108:111], v[216:219], v[232:235], v[108:111]
	v_mfma_f32_16x16x32_bf16 v[92:95], v[216:219], v[244:247], v[92:95]
	s_waitcnt lgkmcnt(4)
	v_mfma_f32_16x16x32_bf16 v[104:107], v[220:223], v[232:235], v[104:107]
	v_mfma_f32_16x16x32_bf16 v[88:91], v[220:223], v[244:247], v[88:91]
	s_waitcnt lgkmcnt(3)
	v_mfma_f32_16x16x32_bf16 v[100:103], v[224:227], v[232:235], v[100:103]
	v_mfma_f32_16x16x32_bf16 v[84:87], v[224:227], v[244:247], v[84:87]
	s_waitcnt lgkmcnt(2)
	v_mfma_f32_16x16x32_bf16 v[96:99], v[228:231], v[232:235], v[96:99]
	v_mfma_f32_16x16x32_bf16 v[80:83], v[228:231], v[244:247], v[80:83]
	s_waitcnt lgkmcnt(1)
	v_mfma_f32_16x16x32_bf16 v[76:79], v[216:219], v[248:251], v[76:79]
	v_mfma_f32_16x16x32_bf16 v[72:75], v[220:223], v[248:251], v[72:75]
	v_mfma_f32_16x16x32_bf16 v[68:71], v[224:227], v[248:251], v[68:71]
	v_mfma_f32_16x16x32_bf16 v[64:67], v[228:231], v[248:251], v[64:67]
	s_waitcnt vmcnt(0)
	s_waitcnt lgkmcnt(0)
	s_barrier
	v_mfma_f32_16x16x32_bf16 v[60:63], v[216:219], v[252:255], v[60:63]
	v_mfma_f32_16x16x32_bf16 v[56:59], v[220:223], v[252:255], v[56:59]
	v_mfma_f32_16x16x32_bf16 v[52:55], v[224:227], v[252:255], v[52:55]
	v_mfma_f32_16x16x32_bf16 v[48:51], v[228:231], v[252:255], v[48:51]
	v_xor_b32_e32 v176, 0x4000, v176
	v_xor_b32_e32 v243, 0x4000, v243
	s_add_i32 s33, s33, 64
	s_andn2_b64 vcc, exec, s[28:29]
	s_mov_b32 s85, 0x800000
	s_cbranch_vccz .LBB0_36
	s_branch .LBB0_41

.LBB0_56:
	s_andn2_b64 vcc, exec, s[24:25]
	s_cbranch_vccnz .LBB0_138
	v_readlane_b32 s0, v236, 47
	s_cmp_lt_i32 s0, 6
	s_mov_b64 s[24:25], -1
	s_cbranch_scc1 .LBB0_105
	v_readlane_b32 s0, v236, 47
	s_cmp_gt_i32 s0, 6
	s_cbranch_scc0 .LBB0_75
	s_waitcnt lgkmcnt(2)
	v_mov_b32_e32 v48, v184
	s_mov_b32 s24, s87
	s_and_b32 s25, s24, 7
	v_readlane_b32 s0, v236, 16
	s_mul_i32 s25, s25, s0
	s_ashr_i32 s24, s24, 3
	s_add_i32 s28, s25, s24
	s_mov_b32 s84, 0x30000
	s_mov_b32 s33, 0x20000
	s_cmp_ge_i32 s28, s18
	s_cbranch_scc1 .LBB0_74
	v_readlane_b32 s0, v236, 37
	v_readlane_b32 s1, v236, 38
	s_cmp_eq_u32 s0, 0
	v_readlane_b32 s52, v240, 18
	v_readlane_b32 s0, v239, 18
	v_readlane_b32 s53, v240, 19
	v_readlane_b32 s4, v239, 22
	v_readlane_b32 s5, v239, 23
	s_cselect_b32 s25, s53, s5
	s_cselect_b32 s24, s52, s4
	s_lshl_b64 s[34:35], s[40:41], 2
	s_add_u32 s24, s24, s34
	s_addc_u32 s25, s25, s35
	s_add_u32 s36, s4, s34
	s_addc_u32 s37, s5, s35
	s_ashr_i32 s26, s28, 31
	s_lshr_b32 s26, s26, 26
	s_add_i32 s26, s28, s26
	s_ashr_i32 s29, s26, 6
	s_andn2_b32 s26, s26, 63
	s_sub_i32 s26, s28, s26
	s_lshl_b32 s29, s29, 3
	s_ashr_i32 s34, s26, 3
	s_and_b32 s26, s28, 7
	v_readlane_b32 s1, v239, 19
	v_readlane_b32 s2, v239, 20
	v_readlane_b32 s3, v239, 21
	v_readlane_b32 s6, v239, 24
	v_readlane_b32 s7, v239, 25
	v_readlane_b32 s8, v239, 26
	v_readlane_b32 s9, v239, 27
	v_readlane_b32 s10, v239, 28
	v_readlane_b32 s11, v239, 29
	v_readlane_b32 s12, v239, 30
	v_readlane_b32 s13, v239, 31
	v_readlane_b32 s14, v239, 32
	v_readlane_b32 s15, v239, 33
	s_or_b32 s38, s29, s26
	s_ashr_i32 s39, s38, 31
	v_readlane_b32 s0, v237, 30
	s_waitcnt vmcnt(17)
	v_mov_b32_e32 v4, v184
	s_lshl_b64 s[38:39], s[38:39], 19
	v_readlane_b32 s10, v237, 40
	v_readlane_b32 s11, v237, 41
	v_ashrrev_i32_e32 v0, 3, v4
	s_add_u32 s38, s10, s38
	v_ashrrev_i32_e32 v1, 31, v0
	s_addc_u32 s39, s11, s39
	v_lshlrev_b64 v[0:1], 11, v[0:1]
	v_lshlrev_b32_e32 v4, 4, v4
	v_readlane_b32 s1, v237, 31
	v_lshl_add_u64 v[2:3], s[38:39], 0, v[0:1]
	v_and_b32_e32 v176, 0x70, v4
	s_mov_b32 s1, 0x10000
	s_waitcnt vmcnt(16)
	v_lshl_add_u64 v[28:29], v[2:3], 0, v[176:177]
	v_add_co_u32_e32 v4, vcc, s1, v28
	s_mov_b32 s0, 0x40000
	s_nop 0
	v_addc_co_u32_e32 v5, vcc, 0, v29, vcc
	v_add_co_u32_e32 v8, vcc, s33, v28
	v_readlane_b32 s54, v240, 20
	s_nop 0
	v_addc_co_u32_e32 v9, vcc, 0, v29, vcc
	v_add_co_u32_e32 v12, vcc, s84, v28
	v_readlane_b32 s55, v240, 21
	s_nop 0
	v_addc_co_u32_e32 v13, vcc, 0, v29, vcc
	s_waitcnt lgkmcnt(0)
	v_add_co_u32_e32 v16, vcc, s0, v28
	s_ashr_i32 s35, s34, 31
	v_readlane_b32 s40, v239, 34
	v_addc_co_u32_e32 v17, vcc, 0, v29, vcc
	s_mov_b32 s0, 0x50000
	s_lshl_b64 s[34:35], s[34:35], 18
	v_readlane_b32 s46, v239, 40
	v_add_co_u32_e32 v20, vcc, s0, v28
	v_readlane_b32 s47, v239, 41
	s_add_u32 s34, s46, s34
	v_addc_co_u32_e32 v21, vcc, 0, v29, vcc
	s_addc_u32 s35, s47, s35
	v_add_co_u32_e32 v24, vcc, 0x60000, v28
	v_lshl_add_u64 v[0:1], s[34:35], 0, v[0:1]
	s_nop 0
	v_addc_co_u32_e32 v25, vcc, 0, v29, vcc
	s_waitcnt vmcnt(32)
	v_lshl_add_u64 v[44:45], v[0:1], 0, v[176:177]
	s_mov_b32 m0, -1
	global_load_dwordx4 v[0:3], v[28:29], off
	v_add_co_u32_e32 v28, vcc, 0x70000, v28
	global_load_dwordx4 v[4:7], v[4:5], off
	s_nop 0
	global_load_dwordx4 v[8:11], v[8:9], off
	v_addc_co_u32_e32 v29, vcc, 0, v29, vcc
	v_add_co_u32_e32 v36, vcc, s1, v44
	global_load_dwordx4 v[12:15], v[12:13], off
	s_nop 0
	global_load_dwordx4 v[16:19], v[16:17], off
	v_addc_co_u32_e32 v37, vcc, 0, v45, vcc
	v_add_co_u32_e32 v40, vcc, 0x20000, v44
	global_load_dwordx4 v[20:23], v[20:21], off
	s_nop 0
	global_load_dwordx4 v[24:27], v[24:25], off
	v_addc_co_u32_e32 v41, vcc, 0, v45, vcc
	global_load_dwordx4 v[28:31], v[28:29], off
	s_nop 0
	global_load_dwordx4 v[32:35], v[44:45], off
	v_add_co_u32_e32 v44, vcc, 0x30000, v44
	global_load_dwordx4 v[36:39], v[36:37], off
	s_nop 0
	global_load_dwordx4 v[40:43], v[40:41], off
	v_addc_co_u32_e32 v45, vcc, 0, v45, vcc
	global_load_dwordx4 v[44:47], v[44:45], off
	s_waitcnt vmcnt(27)
	v_lshrrev_b32_e32 v49, 2, v48
	v_and_b32_e32 v49, 12, v49
	v_and_b32_e32 v179, 0xffffff8f, v48
	v_and_or_b32 v213, v48, 64, v49
	v_readlane_b32 s56, v240, 22
	v_readlane_b32 s57, v240, 23
	v_readlane_b32 s58, v240, 24
	v_readlane_b32 s59, v240, 25
	v_readlane_b32 s60, v240, 26
	v_readlane_b32 s61, v240, 27
	v_readlane_b32 s62, v240, 28
	v_readlane_b32 s63, v240, 29
	v_readlane_b32 s64, v240, 30
	v_readlane_b32 s65, v240, 31
	v_readlane_b32 s66, v240, 32
	v_readlane_b32 s67, v240, 33
	v_readlane_b32 s2, v237, 32
	v_readlane_b32 s3, v237, 33
	v_readlane_b32 s4, v237, 34
	v_readlane_b32 s5, v237, 35
	v_readlane_b32 s6, v237, 36
	v_readlane_b32 s7, v237, 37
	v_readlane_b32 s8, v237, 38
	v_readlane_b32 s9, v237, 39
	v_readlane_b32 s12, v237, 42
	v_readlane_b32 s13, v237, 43
	v_readlane_b32 s14, v237, 44
	v_readlane_b32 s15, v237, 45
	v_readlane_b32 s41, v239, 35
	v_readlane_b32 s42, v239, 36
	v_readlane_b32 s43, v239, 37
	v_readlane_b32 s44, v239, 38
	v_readlane_b32 s45, v239, 39
	v_readlane_b32 s48, v239, 42
	v_readlane_b32 s49, v239, 43
	v_readlane_b32 s50, v239, 44
	v_readlane_b32 s51, v239, 45
	v_readlane_b32 s52, v239, 46
	v_readlane_b32 s53, v239, 47
	v_readlane_b32 s54, v239, 48
	v_readlane_b32 s55, v239, 49
	s_branch .LBB0_62

.LBB0_66:
	s_cmpk_gt_u32 s33, 0x3bf
	s_cselect_b64 s[28:29], -1, 0
	s_cmp_lg_u32 s33, 0
	s_cbranch_scc1 .Ls_nosetup_wout
	v_add_u32_e32 v176, v182, v180
	v_add_u32_e32 v243, v182, v183
	v_add_u32_e32 v241, v181, v180
	v_add_u32_e32 v242, v181, v183
	v_lshrrev_b32_e32 v180, 3, v184
	v_and_b32_e32 v181, 7, v184
	v_bfe_u32 v183, v184, 4, 3
	v_xor_b32_e32 v181, v181, v183
	v_lshlrev_b32_e32 v180, 11, v180
	v_lshl_add_u32 v180, v181, 4, v180
	v_readfirstlane_b32 s100, v184
	s_lshl_b32 s100, s100, 4
	s_cmp_lg_u32 m0, -1
	s_cbranch_scc1 .Ls_nosetup_wout
	s_mov_b32 m0, 0
	s_waitcnt vmcnt(0)
	ds_write_b128 v214, v[0:3]
	ds_write_b128 v214, v[4:7] offset:4096
	ds_write_b128 v214, v[8:11] offset:8192
	ds_write_b128 v214, v[12:15] offset:12288
	ds_write_b128 v214, v[16:19] offset:16384
	ds_write_b128 v214, v[20:23] offset:20480
	ds_write_b128 v214, v[24:27] offset:24576
	ds_write_b128 v214, v[28:31] offset:28672
	ds_write_b128 v214, v[32:35] offset:32768
	ds_write_b128 v214, v[36:39] offset:36864
	ds_write_b128 v214, v[40:43] offset:40960
	ds_write_b128 v214, v[44:47] offset:45056
	s_waitcnt lgkmcnt(0)
	s_barrier
.Ls_nosetup_wout:
	s_lshl_b32 s101, s33, 1
	s_add_u32 s84, s50, s101
	s_addc_u32 s85, s51, 0
	s_add_i32 s101, s33, 64
	s_cmpk_ge_u32 s101, 0x400
	s_cselect_b32 s98, 0x400, 0
	s_cselect_b32 s99, s94, 0
	s_sub_u32 s101, s101, s98
	s_lshl_b32 s101, s101, 1
	s_cmp_lg_u32 s99, 0
	s_cselect_b64 s[86:87], s[40:41], s[50:51]
	s_cselect_b64 s[34:35], s[42:43], s[92:93]
	s_add_u32 s86, s86, s101
	s_addc_u32 s87, s87, 0
	s_add_u32 s34, s34, s101
	s_addc_u32 s35, s35, 0
	s_lshr_b32 s101, s33, 6
	s_add_i32 s101, s101, 1
	s_and_b32 s101, s101, 1
	s_lshl_b32 s101, s101, 14
	s_add_u32 s101, s101, s100
	s_add_u32 s101, s101, 0x8000
	s_add_u32 s98, s84, 0x20000
	s_addc_u32 s99, s85, 0
	s_add_u32 m0, s100, 0x2000
	s_nop 0
	global_load_lds_dwordx4 v180, s[98:99]
	s_add_u32 s98, s84, 0x30000
	s_addc_u32 s99, s85, 0
	s_add_u32 m0, s100, 0x3000
	s_nop 0
	global_load_lds_dwordx4 v180, s[98:99]
	s_add_u32 s98, s84, 0x60000
	s_addc_u32 s99, s85, 0
	s_add_u32 m0, s100, 0x6000
	s_nop 0
	global_load_lds_dwordx4 v180, s[98:99]
	s_add_u32 s98, s84, 0x70000
	s_addc_u32 s99, s85, 0
	s_add_u32 m0, s100, 0x7000
	s_nop 0
	global_load_lds_dwordx4 v180, s[98:99]
	s_add_u32 s98, s34, 0x0
	s_addc_u32 s99, s35, 0
	s_add_u32 m0, s101, 0x0
	s_nop 0
	global_load_lds_dwordx4 v180, s[98:99]
	s_add_u32 s98, s34, 0x10000
	s_addc_u32 s99, s35, 0
	s_add_u32 m0, s101, 0x1000
	s_nop 0
	global_load_lds_dwordx4 v180, s[98:99]
	ds_read_b128 v[216:219], v176 offset:32768
	ds_read_b128 v[232:235], v241
	ds_read_b128 v[220:223], v176 offset:34816
	ds_read_b128 v[224:227], v176 offset:36864
	ds_read_b128 v[228:231], v176 offset:38912
	ds_read_b128 v[244:247], v241 offset:2048
	ds_read_b128 v[248:251], v241 offset:4096
	ds_read_b128 v[252:255], v241 offset:6144
	s_waitcnt lgkmcnt(6)
	v_mfma_f32_16x16x32_bf16 v[172:175], v[216:219], v[232:235], v[172:175]
	s_waitcnt lgkmcnt(5)
	v_mfma_f32_16x16x32_bf16 v[168:171], v[220:223], v[232:235], v[168:171]
	s_waitcnt lgkmcnt(4)
	v_mfma_f32_16x16x32_bf16 v[164:167], v[224:227], v[232:235], v[164:167]
	s_waitcnt lgkmcnt(3)
	v_mfma_f32_16x16x32_bf16 v[160:163], v[228:231], v[232:235], v[160:163]
	ds_read_b128 v[232:235], v242
	s_waitcnt lgkmcnt(3)
	v_mfma_f32_16x16x32_bf16 v[156:159], v[216:219], v[244:247], v[156:159]
	v_mfma_f32_16x16x32_bf16 v[152:155], v[220:223], v[244:247], v[152:155]
	v_mfma_f32_16x16x32_bf16 v[148:151], v[224:227], v[244:247], v[148:151]
	v_mfma_f32_16x16x32_bf16 v[144:147], v[228:231], v[244:247], v[144:147]
	ds_read_b128 v[244:247], v242 offset:2048
	s_waitcnt lgkmcnt(3)
	v_mfma_f32_16x16x32_bf16 v[140:143], v[216:219], v[248:251], v[140:143]
	s_waitcnt lgkmcnt(2)
	v_mfma_f32_16x16x32_bf16 v[124:127], v[216:219], v[252:255], v[124:127]
	ds_read_b128 v[216:219], v243 offset:32768
	v_mfma_f32_16x16x32_bf16 v[136:139], v[220:223], v[248:251], v[136:139]
	v_mfma_f32_16x16x32_bf16 v[120:123], v[220:223], v[252:255], v[120:123]
	ds_read_b128 v[220:223], v243 offset:34816
	v_mfma_f32_16x16x32_bf16 v[132:135], v[224:227], v[248:251], v[132:135]
	v_mfma_f32_16x16x32_bf16 v[116:119], v[224:227], v[252:255], v[116:119]
	ds_read_b128 v[224:227], v243 offset:36864
	v_mfma_f32_16x16x32_bf16 v[128:131], v[228:231], v[248:251], v[128:131]
	v_mfma_f32_16x16x32_bf16 v[112:115], v[228:231], v[252:255], v[112:115]
	ds_read_b128 v[228:231], v243 offset:38912
	ds_read_b128 v[248:251], v242 offset:4096
	ds_read_b128 v[252:255], v242 offset:6144
	s_waitcnt lgkmcnt(5)
	v_mfma_f32_16x16x32_bf16 v[172:175], v[216:219], v[232:235], v[172:175]
	v_mfma_f32_16x16x32_bf16 v[156:159], v[216:219], v[244:247], v[156:159]
	s_waitcnt lgkmcnt(4)
	v_mfma_f32_16x16x32_bf16 v[168:171], v[220:223], v[232:235], v[168:171]
	v_mfma_f32_16x16x32_bf16 v[152:155], v[220:223], v[244:247], v[152:155]
	s_waitcnt lgkmcnt(3)
	v_mfma_f32_16x16x32_bf16 v[164:167], v[224:227], v[232:235], v[164:167]
	v_mfma_f32_16x16x32_bf16 v[148:151], v[224:227], v[244:247], v[148:151]
	s_waitcnt lgkmcnt(2)
	v_mfma_f32_16x16x32_bf16 v[160:163], v[228:231], v[232:235], v[160:163]
	v_mfma_f32_16x16x32_bf16 v[144:147], v[228:231], v[244:247], v[144:147]
	s_waitcnt lgkmcnt(1)
	v_mfma_f32_16x16x32_bf16 v[140:143], v[216:219], v[248:251], v[140:143]
	v_mfma_f32_16x16x32_bf16 v[136:139], v[220:223], v[248:251], v[136:139]
	v_mfma_f32_16x16x32_bf16 v[132:135], v[224:227], v[248:251], v[132:135]
	v_mfma_f32_16x16x32_bf16 v[128:131], v[228:231], v[248:251], v[128:131]
	s_waitcnt vmcnt(0)
	s_waitcnt lgkmcnt(0)
	s_barrier
	v_mfma_f32_16x16x32_bf16 v[124:127], v[216:219], v[252:255], v[124:127]
	v_mfma_f32_16x16x32_bf16 v[120:123], v[220:223], v[252:255], v[120:123]
	v_mfma_f32_16x16x32_bf16 v[116:119], v[224:227], v[252:255], v[116:119]
	v_mfma_f32_16x16x32_bf16 v[112:115], v[228:231], v[252:255], v[112:115]
	s_add_u32 s98, s86, 0x0
	s_addc_u32 s99, s87, 0
	s_add_u32 m0, s100, 0x0
	s_nop 0
	global_load_lds_dwordx4 v180, s[98:99]
	s_add_u32 s98, s86, 0x10000
	s_addc_u32 s99, s87, 0
	s_add_u32 m0, s100, 0x1000
	s_nop 0
	global_load_lds_dwordx4 v180, s[98:99]
	s_add_u32 s98, s86, 0x40000
	s_addc_u32 s99, s87, 0
	s_add_u32 m0, s100, 0x4000
	s_nop 0
	global_load_lds_dwordx4 v180, s[98:99]
	s_add_u32 s98, s86, 0x50000
	s_addc_u32 s99, s87, 0
	s_add_u32 m0, s100, 0x5000
	s_nop 0
	global_load_lds_dwordx4 v180, s[98:99]
	s_add_u32 s98, s34, 0x20000
	s_addc_u32 s99, s35, 0
	s_add_u32 m0, s101, 0x2000
	s_nop 0
	global_load_lds_dwordx4 v180, s[98:99]
	s_add_u32 s98, s34, 0x30000
	s_addc_u32 s99, s35, 0
	s_add_u32 m0, s101, 0x3000
	s_nop 0
	global_load_lds_dwordx4 v180, s[98:99]
	ds_read_b128 v[216:219], v176 offset:32768
	ds_read_b128 v[232:235], v241 offset:8192
	ds_read_b128 v[220:223], v176 offset:34816
	ds_read_b128 v[224:227], v176 offset:36864
	ds_read_b128 v[228:231], v176 offset:38912
	ds_read_b128 v[244:247], v241 offset:10240
	ds_read_b128 v[248:251], v241 offset:12288
	ds_read_b128 v[252:255], v241 offset:14336
	s_waitcnt lgkmcnt(6)
	v_mfma_f32_16x16x32_bf16 v[108:111], v[216:219], v[232:235], v[108:111]
	s_waitcnt lgkmcnt(5)
	v_mfma_f32_16x16x32_bf16 v[104:107], v[220:223], v[232:235], v[104:107]
	s_waitcnt lgkmcnt(4)
	v_mfma_f32_16x16x32_bf16 v[100:103], v[224:227], v[232:235], v[100:103]
	s_waitcnt lgkmcnt(3)
	v_mfma_f32_16x16x32_bf16 v[96:99], v[228:231], v[232:235], v[96:99]
	ds_read_b128 v[232:235], v242 offset:8192
	s_waitcnt lgkmcnt(3)
	v_mfma_f32_16x16x32_bf16 v[92:95], v[216:219], v[244:247], v[92:95]
	v_mfma_f32_16x16x32_bf16 v[88:91], v[220:223], v[244:247], v[88:91]
	v_mfma_f32_16x16x32_bf16 v[84:87], v[224:227], v[244:247], v[84:87]
	v_mfma_f32_16x16x32_bf16 v[80:83], v[228:231], v[244:247], v[80:83]
	ds_read_b128 v[244:247], v242 offset:10240
	s_waitcnt lgkmcnt(3)
	v_mfma_f32_16x16x32_bf16 v[76:79], v[216:219], v[248:251], v[76:79]
	s_waitcnt lgkmcnt(2)
	v_mfma_f32_16x16x32_bf16 v[60:63], v[216:219], v[252:255], v[60:63]
	ds_read_b128 v[216:219], v243 offset:32768
	v_mfma_f32_16x16x32_bf16 v[72:75], v[220:223], v[248:251], v[72:75]
	v_mfma_f32_16x16x32_bf16 v[56:59], v[220:223], v[252:255], v[56:59]
	ds_read_b128 v[220:223], v243 offset:34816
	v_mfma_f32_16x16x32_bf16 v[68:71], v[224:227], v[248:251], v[68:71]
	v_mfma_f32_16x16x32_bf16 v[52:55], v[224:227], v[252:255], v[52:55]
	ds_read_b128 v[224:227], v243 offset:36864
	v_mfma_f32_16x16x32_bf16 v[64:67], v[228:231], v[248:251], v[64:67]
	v_mfma_f32_16x16x32_bf16 v[48:51], v[228:231], v[252:255], v[48:51]
	ds_read_b128 v[228:231], v243 offset:38912
	ds_read_b128 v[248:251], v242 offset:12288
	ds_read_b128 v[252:255], v242 offset:14336
	s_waitcnt lgkmcnt(5)
	v_mfma_f32_16x16x32_bf16 v[108:111], v[216:219], v[232:235], v[108:111]
	v_mfma_f32_16x16x32_bf16 v[92:95], v[216:219], v[244:247], v[92:95]
	s_waitcnt lgkmcnt(4)
	v_mfma_f32_16x16x32_bf16 v[104:107], v[220:223], v[232:235], v[104:107]
	v_mfma_f32_16x16x32_bf16 v[88:91], v[220:223], v[244:247], v[88:91]
	s_waitcnt lgkmcnt(3)
	v_mfma_f32_16x16x32_bf16 v[100:103], v[224:227], v[232:235], v[100:103]
	v_mfma_f32_16x16x32_bf16 v[84:87], v[224:227], v[244:247], v[84:87]
	s_waitcnt lgkmcnt(2)
	v_mfma_f32_16x16x32_bf16 v[96:99], v[228:231], v[232:235], v[96:99]
	v_mfma_f32_16x16x32_bf16 v[80:83], v[228:231], v[244:247], v[80:83]
	s_waitcnt lgkmcnt(1)
	v_mfma_f32_16x16x32_bf16 v[76:79], v[216:219], v[248:251], v[76:79]
	v_mfma_f32_16x16x32_bf16 v[72:75], v[220:223], v[248:251], v[72:75]
	v_mfma_f32_16x16x32_bf16 v[68:71], v[224:227], v[248:251], v[68:71]
	v_mfma_f32_16x16x32_bf16 v[64:67], v[228:231], v[248:251], v[64:67]
	s_waitcnt vmcnt(0)
	s_waitcnt lgkmcnt(0)
	s_barrier
	v_mfma_f32_16x16x32_bf16 v[60:63], v[216:219], v[252:255], v[60:63]
	v_mfma_f32_16x16x32_bf16 v[56:59], v[220:223], v[252:255], v[56:59]
	v_mfma_f32_16x16x32_bf16 v[52:55], v[224:227], v[252:255], v[52:55]
	v_mfma_f32_16x16x32_bf16 v[48:51], v[228:231], v[252:255], v[48:51]
	v_xor_b32_e32 v176, 0x4000, v176
	v_xor_b32_e32 v243, 0x4000, v243
	s_add_i32 s33, s33, 64
	s_andn2_b64 vcc, exec, s[28:29]
	s_mov_b32 s85, 0x800000
	s_cbranch_vccz .LBB0_61
	s_branch .LBB0_66
